# dead-copy elimination in the P3 epilogue: reads of 8 accumulator-pair copies renamed to the accumulators, copies dropped
# baseline (speedup 1.0000x reference)
.LBB0_385:
	v_mov_b32_e32 v140, v144
	s_lshl_b32 s9, s44, 8
	v_readfirstlane_b32 s8, v140
	s_bfe_u32 s29, s8, 0x20006
	s_ashr_i32 s8, s8, 2
	s_andn2_b32 s8, s8, 63
	s_add_i32 s8, s8, s9
	v_and_or_b32 v142, v140, 15, s8
	s_lshl_b32 s8, s20, 8
	s_lshl_b32 s9, s29, 6
	v_bfe_u32 v149, v140, 4, 2
	s_or_b32 s8, s9, s8
	v_lshl_or_b32 v140, v149, 3, s8
	v_ashrrev_i32_e32 v143, 31, v142
	v_ashrrev_i32_e32 v141, 31, v140
	v_lshlrev_b64 v[150:151], 10, v[142:143]
	v_lshl_add_u64 v[158:159], v[150:151], 0, v[140:141]
	v_lshl_add_u64 v[160:161], v[158:159], 2, s[12:13]
	v_lshl_add_u64 v[158:159], v[158:159], 1, s[16:17]
	s_lshl_b32 s44, s20, 2
	v_cmp_eq_u32_e32 vcc, 0, v149
	s_ashr_i32 s45, s44, 31
	v_mov_b64_e32 v[152:153], v[126:127]
	v_mov_b64_e32 v[156:157], v[122:123]
	v_mov_b64_e32 v[154:155], v[120:121]
	v_cvt_pk_bf16_f32 v120, v124, v125
	v_cvt_pk_bf16_f32 v121, v152, v153
	v_cvt_pk_bf16_f32 v122, v154, v155
	v_cvt_pk_bf16_f32 v123, v156, v157
	global_store_dwordx4 v[158:159], v[120:123], off
	s_nop 0
	v_mul_f32_e32 v151, v125, v125
	v_mul_f32_e32 v153, v153, v153
	v_mul_f32_e32 v155, v155, v155
	v_mul_f32_e32 v157, v157, v157
	v_fmac_f32_e32 v151, v124, v124
	v_fmac_f32_e32 v153, v152, v152
	v_fmac_f32_e32 v155, v154, v154
	v_fmac_f32_e32 v157, v156, v156
	v_add_f32_e32 v150, v151, v153
	v_add_f32_e32 v151, v155, v157
	v_add_f32_e32 v150, v150, v151
	v_mov_b64_e32 v[120:121], v[114:115]
	v_mov_b64_e32 v[122:123], v[112:113]
	v_mul_f32_e32 v112, v117, v117
	v_mul_f32_e32 v113, v119, v119
	v_mul_f32_e32 v114, v123, v123
	v_mul_f32_e32 v115, v121, v121
	v_fmac_f32_e32 v112, v116, v116
	v_fmac_f32_e32 v113, v118, v118
	v_fmac_f32_e32 v114, v122, v122
	v_fmac_f32_e32 v115, v120, v120
	v_add_f32_e32 v112, v112, v113
	v_add_f32_e32 v113, v114, v115
	v_add_f32_e32 v112, v112, v113
	v_add_f32_e32 v112, v150, v112
	ds_bpermute_b32 v113, v193, v112
	v_cvt_pk_bf16_f32 v114, v116, v117
	v_cvt_pk_bf16_f32 v115, v118, v119
	v_cvt_pk_bf16_f32 v116, v122, v123
	v_cvt_pk_bf16_f32 v117, v120, v121
	s_waitcnt lgkmcnt(0)
	v_add_f32_e32 v112, v112, v113
	ds_bpermute_b32 v113, v194, v112
	global_store_dwordx4 v[158:159], v[114:117], off offset:64
	s_and_saveexec_b64 s[46:47], vcc
	s_cbranch_execz .LBB0_387
	v_lshlrev_b64 v[114:115], 6, v[142:143]
	v_lshl_add_u64 v[114:115], s[6:7], 0, v[114:115]
	v_lshl_add_u64 v[114:115], s[44:45], 2, v[114:115]
	s_lshl_b32 s20, s29, 2
	v_lshl_add_u64 v[114:115], v[114:115], 0, s[20:21]
	s_waitcnt lgkmcnt(0)
	v_add_f32_e32 v112, v112, v113
	global_store_dword v[114:115], v112, off
.LBB0_387:
	s_or_b64 exec, exec, s[46:47]
	v_or_b32_e32 v112, 16, v142
	s_waitcnt lgkmcnt(0)
	v_ashrrev_i32_e32 v113, 31, v112
	v_lshlrev_b64 v[114:115], 10, v[112:113]
	v_lshl_add_u64 v[122:123], v[114:115], 0, v[140:141]
	v_lshl_add_u64 v[124:125], v[122:123], 2, s[12:13]
	v_lshl_add_u64 v[122:123], v[122:123], 1, s[16:17]
	v_mov_b64_e32 v[116:117], v[110:111]
	v_mov_b64_e32 v[120:121], v[106:107]
	v_mov_b64_e32 v[118:119], v[104:105]
	v_cvt_pk_bf16_f32 v104, v108, v109
	v_cvt_pk_bf16_f32 v105, v116, v117
	v_cvt_pk_bf16_f32 v106, v118, v119
	v_cvt_pk_bf16_f32 v107, v120, v121
	global_store_dwordx4 v[122:123], v[104:107], off
	s_nop 0
	v_mul_f32_e32 v115, v109, v109
	v_mul_f32_e32 v117, v117, v117
	v_mul_f32_e32 v119, v119, v119
	v_mul_f32_e32 v121, v121, v121
	v_fmac_f32_e32 v115, v108, v108
	v_fmac_f32_e32 v117, v116, v116
	v_fmac_f32_e32 v119, v118, v118
	v_fmac_f32_e32 v121, v120, v120
	v_add_f32_e32 v114, v115, v117
	v_add_f32_e32 v115, v119, v121
	v_add_f32_e32 v114, v114, v115
	v_mov_b64_e32 v[104:105], v[98:99]
	v_mov_b64_e32 v[106:107], v[96:97]
	v_mul_f32_e32 v96, v101, v101
	v_mul_f32_e32 v97, v103, v103
	v_mul_f32_e32 v98, v107, v107
	v_mul_f32_e32 v99, v105, v105
	v_fmac_f32_e32 v96, v100, v100
	v_fmac_f32_e32 v97, v102, v102
	v_fmac_f32_e32 v98, v106, v106
	v_fmac_f32_e32 v99, v104, v104
	v_add_f32_e32 v96, v96, v97
	v_add_f32_e32 v97, v98, v99
	v_add_f32_e32 v96, v96, v97
	v_add_f32_e32 v96, v114, v96
	ds_bpermute_b32 v97, v193, v96
	v_cvt_pk_bf16_f32 v98, v100, v101
	v_cvt_pk_bf16_f32 v99, v102, v103
	v_cvt_pk_bf16_f32 v100, v106, v107
	v_cvt_pk_bf16_f32 v101, v104, v105
	s_waitcnt lgkmcnt(0)
	v_add_f32_e32 v96, v96, v97
	ds_bpermute_b32 v97, v194, v96
	global_store_dwordx4 v[122:123], v[98:101], off offset:64
	s_and_saveexec_b64 s[46:47], vcc
	s_cbranch_execz .LBB0_389
	v_lshlrev_b64 v[98:99], 6, v[112:113]
	v_lshl_add_u64 v[98:99], s[6:7], 0, v[98:99]
	v_lshl_add_u64 v[98:99], s[44:45], 2, v[98:99]
	s_lshl_b32 s20, s29, 2
	v_lshl_add_u64 v[98:99], v[98:99], 0, s[20:21]
	s_waitcnt lgkmcnt(0)
	v_add_f32_e32 v96, v96, v97
	global_store_dword v[98:99], v96, off
.LBB0_389:
	s_or_b64 exec, exec, s[46:47]
	v_or_b32_e32 v96, 32, v142
	s_waitcnt lgkmcnt(0)
	v_ashrrev_i32_e32 v97, 31, v96
	v_lshlrev_b64 v[98:99], 10, v[96:97]
	v_lshl_add_u64 v[106:107], v[98:99], 0, v[140:141]
	v_lshl_add_u64 v[108:109], v[106:107], 2, s[12:13]
	v_lshl_add_u64 v[106:107], v[106:107], 1, s[16:17]
	v_mov_b64_e32 v[100:101], v[94:95]
	v_mov_b64_e32 v[104:105], v[90:91]
	v_mov_b64_e32 v[102:103], v[88:89]
	v_cvt_pk_bf16_f32 v88, v92, v93
	v_cvt_pk_bf16_f32 v89, v100, v101
	v_cvt_pk_bf16_f32 v90, v102, v103
	v_cvt_pk_bf16_f32 v91, v104, v105
	global_store_dwordx4 v[106:107], v[88:91], off
	s_nop 0
	v_mul_f32_e32 v99, v93, v93
	v_mul_f32_e32 v101, v101, v101
	v_mul_f32_e32 v103, v103, v103
	v_mul_f32_e32 v105, v105, v105
	v_fmac_f32_e32 v99, v92, v92
	v_fmac_f32_e32 v101, v100, v100
	v_fmac_f32_e32 v103, v102, v102
	v_fmac_f32_e32 v105, v104, v104
	v_add_f32_e32 v98, v99, v101
	v_add_f32_e32 v99, v103, v105
	v_add_f32_e32 v98, v98, v99
	v_mov_b64_e32 v[88:89], v[82:83]
	v_mov_b64_e32 v[90:91], v[80:81]
	v_mul_f32_e32 v80, v85, v85
	v_mul_f32_e32 v81, v87, v87
	v_mul_f32_e32 v82, v91, v91
	v_mul_f32_e32 v83, v89, v89
	v_fmac_f32_e32 v80, v84, v84
	v_fmac_f32_e32 v81, v86, v86
	v_fmac_f32_e32 v82, v90, v90
	v_fmac_f32_e32 v83, v88, v88
	v_add_f32_e32 v80, v80, v81
	v_add_f32_e32 v81, v82, v83
	v_add_f32_e32 v80, v80, v81
	v_add_f32_e32 v80, v98, v80
	ds_bpermute_b32 v81, v193, v80
	v_cvt_pk_bf16_f32 v82, v84, v85
	v_cvt_pk_bf16_f32 v83, v86, v87
	v_cvt_pk_bf16_f32 v84, v90, v91
	v_cvt_pk_bf16_f32 v85, v88, v89
	s_waitcnt lgkmcnt(0)
	v_add_f32_e32 v80, v80, v81
	ds_bpermute_b32 v81, v194, v80
	global_store_dwordx4 v[106:107], v[82:85], off offset:64
	s_and_saveexec_b64 s[46:47], vcc
	s_cbranch_execz .LBB0_391
	v_lshlrev_b64 v[82:83], 6, v[96:97]
	v_lshl_add_u64 v[82:83], s[6:7], 0, v[82:83]
	v_lshl_add_u64 v[82:83], s[44:45], 2, v[82:83]
	s_lshl_b32 s20, s29, 2
	v_lshl_add_u64 v[82:83], v[82:83], 0, s[20:21]
	s_waitcnt lgkmcnt(0)
	v_add_f32_e32 v80, v80, v81
	global_store_dword v[82:83], v80, off
.LBB0_391:
	s_or_b64 exec, exec, s[46:47]
	v_or_b32_e32 v80, 48, v142
	s_waitcnt lgkmcnt(0)
	v_ashrrev_i32_e32 v81, 31, v80
	v_lshlrev_b64 v[82:83], 10, v[80:81]
	v_lshl_add_u64 v[90:91], v[82:83], 0, v[140:141]
	v_lshl_add_u64 v[92:93], v[90:91], 2, s[12:13]
	v_lshl_add_u64 v[90:91], v[90:91], 1, s[16:17]
	v_mov_b64_e32 v[84:85], v[78:79]
	v_mov_b64_e32 v[88:89], v[74:75]
	v_mov_b64_e32 v[86:87], v[72:73]
	v_cvt_pk_bf16_f32 v72, v76, v77
	v_cvt_pk_bf16_f32 v73, v84, v85
	v_cvt_pk_bf16_f32 v74, v86, v87
	v_cvt_pk_bf16_f32 v75, v88, v89
	global_store_dwordx4 v[90:91], v[72:75], off
	s_nop 0
	v_mul_f32_e32 v83, v77, v77
	v_mul_f32_e32 v85, v85, v85
	v_mul_f32_e32 v87, v87, v87
	v_mul_f32_e32 v89, v89, v89
	v_fmac_f32_e32 v83, v76, v76
	v_fmac_f32_e32 v85, v84, v84
	v_fmac_f32_e32 v87, v86, v86
	v_fmac_f32_e32 v89, v88, v88
	v_add_f32_e32 v82, v83, v85
	v_add_f32_e32 v83, v87, v89
	v_add_f32_e32 v82, v82, v83
	v_mov_b64_e32 v[72:73], v[66:67]
	v_mov_b64_e32 v[74:75], v[64:65]
	v_mul_f32_e32 v64, v69, v69
	v_mul_f32_e32 v65, v71, v71
	v_mul_f32_e32 v66, v75, v75
	v_mul_f32_e32 v67, v73, v73
	v_fmac_f32_e32 v64, v68, v68
	v_fmac_f32_e32 v65, v70, v70
	v_fmac_f32_e32 v66, v74, v74
	v_fmac_f32_e32 v67, v72, v72
	v_add_f32_e32 v64, v64, v65
	v_add_f32_e32 v65, v66, v67
	v_add_f32_e32 v64, v64, v65
	v_add_f32_e32 v64, v82, v64
	ds_bpermute_b32 v65, v193, v64
	v_cvt_pk_bf16_f32 v66, v68, v69
	v_cvt_pk_bf16_f32 v67, v70, v71
	v_cvt_pk_bf16_f32 v68, v74, v75
	v_cvt_pk_bf16_f32 v69, v72, v73
	s_waitcnt lgkmcnt(0)
	v_add_f32_e32 v64, v64, v65
	ds_bpermute_b32 v65, v194, v64
	global_store_dwordx4 v[90:91], v[66:69], off offset:64
	s_and_saveexec_b64 s[46:47], vcc
	s_cbranch_execz .LBB0_393
	v_lshlrev_b64 v[66:67], 6, v[80:81]
	v_lshl_add_u64 v[66:67], s[6:7], 0, v[66:67]
	v_lshl_add_u64 v[66:67], s[44:45], 2, v[66:67]
	s_lshl_b32 s20, s29, 2
	v_lshl_add_u64 v[66:67], v[66:67], 0, s[20:21]
	s_waitcnt lgkmcnt(0)
	v_add_f32_e32 v64, v64, v65
	global_store_dword v[66:67], v64, off
.LBB0_393:
	s_or_b64 exec, exec, s[46:47]
	v_add_u32_e32 v64, 0x80, v142
	s_waitcnt lgkmcnt(0)
	v_ashrrev_i32_e32 v65, 31, v64
	v_lshlrev_b64 v[66:67], 10, v[64:65]
	v_lshl_add_u64 v[74:75], v[66:67], 0, v[140:141]
	v_lshl_add_u64 v[76:77], v[74:75], 2, s[12:13]
	v_lshl_add_u64 v[74:75], v[74:75], 1, s[16:17]
	v_mov_b64_e32 v[68:69], v[62:63]
	v_mov_b64_e32 v[72:73], v[58:59]
	v_mov_b64_e32 v[70:71], v[56:57]
	v_cvt_pk_bf16_f32 v56, v60, v61
	v_cvt_pk_bf16_f32 v57, v68, v69
	v_cvt_pk_bf16_f32 v58, v70, v71
	v_cvt_pk_bf16_f32 v59, v72, v73
	global_store_dwordx4 v[74:75], v[56:59], off
	s_nop 0
	v_mul_f32_e32 v67, v61, v61
	v_mul_f32_e32 v69, v69, v69
	v_mul_f32_e32 v71, v71, v71
	v_mul_f32_e32 v73, v73, v73
	v_fmac_f32_e32 v67, v60, v60
	v_fmac_f32_e32 v69, v68, v68
	v_fmac_f32_e32 v71, v70, v70
	v_fmac_f32_e32 v73, v72, v72
	v_add_f32_e32 v66, v67, v69
	v_add_f32_e32 v67, v71, v73
	v_add_f32_e32 v66, v66, v67
	v_mov_b64_e32 v[56:57], v[50:51]
	v_mov_b64_e32 v[58:59], v[48:49]
	v_mul_f32_e32 v48, v53, v53
	v_mul_f32_e32 v49, v55, v55
	v_mul_f32_e32 v50, v59, v59
	v_mul_f32_e32 v51, v57, v57
	v_fmac_f32_e32 v48, v52, v52
	v_fmac_f32_e32 v49, v54, v54
	v_fmac_f32_e32 v50, v58, v58
	v_fmac_f32_e32 v51, v56, v56
	v_add_f32_e32 v48, v48, v49
	v_add_f32_e32 v49, v50, v51
	v_add_f32_e32 v48, v48, v49
	v_add_f32_e32 v48, v66, v48
	ds_bpermute_b32 v49, v193, v48
	v_cvt_pk_bf16_f32 v50, v52, v53
	v_cvt_pk_bf16_f32 v51, v54, v55
	v_cvt_pk_bf16_f32 v52, v58, v59
	v_cvt_pk_bf16_f32 v53, v56, v57
	s_waitcnt lgkmcnt(0)
	v_add_f32_e32 v48, v48, v49
	ds_bpermute_b32 v49, v194, v48
	global_store_dwordx4 v[74:75], v[50:53], off offset:64
	s_and_saveexec_b64 s[46:47], vcc
	s_cbranch_execz .LBB0_395
	v_lshlrev_b64 v[50:51], 6, v[64:65]
	v_lshl_add_u64 v[50:51], s[6:7], 0, v[50:51]
	v_lshl_add_u64 v[50:51], s[44:45], 2, v[50:51]
	s_lshl_b32 s20, s29, 2
	v_lshl_add_u64 v[50:51], v[50:51], 0, s[20:21]
	s_waitcnt lgkmcnt(0)
	v_add_f32_e32 v48, v48, v49
	global_store_dword v[50:51], v48, off
.LBB0_395:
	s_or_b64 exec, exec, s[46:47]
	v_add_u32_e32 v48, 0x90, v142
	s_waitcnt lgkmcnt(0)
	v_ashrrev_i32_e32 v49, 31, v48
	v_lshlrev_b64 v[50:51], 10, v[48:49]
	v_lshl_add_u64 v[58:59], v[50:51], 0, v[140:141]
	v_lshl_add_u64 v[60:61], v[58:59], 2, s[12:13]
	v_lshl_add_u64 v[58:59], v[58:59], 1, s[16:17]
	v_mov_b64_e32 v[52:53], v[46:47]
	v_mov_b64_e32 v[56:57], v[42:43]
	v_mov_b64_e32 v[54:55], v[40:41]
	v_cvt_pk_bf16_f32 v40, v44, v45
	v_cvt_pk_bf16_f32 v41, v52, v53
	v_cvt_pk_bf16_f32 v42, v54, v55
	v_cvt_pk_bf16_f32 v43, v56, v57
	global_store_dwordx4 v[58:59], v[40:43], off
	s_nop 0
	v_mul_f32_e32 v51, v45, v45
	v_mul_f32_e32 v53, v53, v53
	v_mul_f32_e32 v55, v55, v55
	v_mul_f32_e32 v57, v57, v57
	v_fmac_f32_e32 v51, v44, v44
	v_fmac_f32_e32 v53, v52, v52
	v_fmac_f32_e32 v55, v54, v54
	v_fmac_f32_e32 v57, v56, v56
	v_add_f32_e32 v50, v51, v53
	v_add_f32_e32 v51, v55, v57
	v_add_f32_e32 v50, v50, v51
	v_mov_b64_e32 v[40:41], v[34:35]
	v_mov_b64_e32 v[42:43], v[32:33]
	v_mul_f32_e32 v32, v37, v37
	v_mul_f32_e32 v33, v39, v39
	v_mul_f32_e32 v34, v43, v43
	v_mul_f32_e32 v35, v41, v41
	v_fmac_f32_e32 v32, v36, v36
	v_fmac_f32_e32 v33, v38, v38
	v_fmac_f32_e32 v34, v42, v42
	v_fmac_f32_e32 v35, v40, v40
	v_add_f32_e32 v32, v32, v33
	v_add_f32_e32 v33, v34, v35
	v_add_f32_e32 v32, v32, v33
	v_add_f32_e32 v32, v50, v32
	ds_bpermute_b32 v33, v193, v32
	v_cvt_pk_bf16_f32 v34, v36, v37
	v_cvt_pk_bf16_f32 v35, v38, v39
	v_cvt_pk_bf16_f32 v36, v42, v43
	v_cvt_pk_bf16_f32 v37, v40, v41
	s_waitcnt lgkmcnt(0)
	v_add_f32_e32 v32, v32, v33
	ds_bpermute_b32 v33, v194, v32
	global_store_dwordx4 v[58:59], v[34:37], off offset:64
	s_and_saveexec_b64 s[46:47], vcc
	s_cbranch_execz .LBB0_397
	v_lshlrev_b64 v[34:35], 6, v[48:49]
	v_lshl_add_u64 v[34:35], s[6:7], 0, v[34:35]
	v_lshl_add_u64 v[34:35], s[44:45], 2, v[34:35]
	s_lshl_b32 s20, s29, 2
	v_lshl_add_u64 v[34:35], v[34:35], 0, s[20:21]
	s_waitcnt lgkmcnt(0)
	v_add_f32_e32 v32, v32, v33
	global_store_dword v[34:35], v32, off
.LBB0_397:
	s_or_b64 exec, exec, s[46:47]
	v_add_u32_e32 v32, 0xa0, v142
	s_waitcnt lgkmcnt(0)
	v_ashrrev_i32_e32 v33, 31, v32
	v_lshlrev_b64 v[34:35], 10, v[32:33]
	v_lshl_add_u64 v[42:43], v[34:35], 0, v[140:141]
	v_lshl_add_u64 v[44:45], v[42:43], 2, s[12:13]
	v_lshl_add_u64 v[42:43], v[42:43], 1, s[16:17]
	v_mov_b64_e32 v[36:37], v[30:31]
	v_mov_b64_e32 v[40:41], v[26:27]
	v_mov_b64_e32 v[38:39], v[24:25]
	v_cvt_pk_bf16_f32 v24, v28, v29
	v_cvt_pk_bf16_f32 v25, v36, v37
	v_cvt_pk_bf16_f32 v26, v38, v39
	v_cvt_pk_bf16_f32 v27, v40, v41
	global_store_dwordx4 v[42:43], v[24:27], off
	s_nop 0
	v_mul_f32_e32 v35, v29, v29
	v_mul_f32_e32 v37, v37, v37
	v_mul_f32_e32 v39, v39, v39
	v_mul_f32_e32 v41, v41, v41
	v_fmac_f32_e32 v35, v28, v28
	v_fmac_f32_e32 v37, v36, v36
	v_fmac_f32_e32 v39, v38, v38
	v_fmac_f32_e32 v41, v40, v40
	v_add_f32_e32 v34, v35, v37
	v_add_f32_e32 v35, v39, v41
	v_add_f32_e32 v34, v34, v35
	v_mov_b64_e32 v[24:25], v[18:19]
	v_mov_b64_e32 v[26:27], v[16:17]
	v_mul_f32_e32 v16, v21, v21
	v_mul_f32_e32 v17, v23, v23
	v_mul_f32_e32 v18, v27, v27
	v_mul_f32_e32 v19, v25, v25
	v_fmac_f32_e32 v16, v20, v20
	v_fmac_f32_e32 v17, v22, v22
	v_fmac_f32_e32 v18, v26, v26
	v_fmac_f32_e32 v19, v24, v24
	v_add_f32_e32 v16, v16, v17
	v_add_f32_e32 v17, v18, v19
	v_add_f32_e32 v16, v16, v17
	v_add_f32_e32 v16, v34, v16
	ds_bpermute_b32 v17, v193, v16
	v_cvt_pk_bf16_f32 v18, v20, v21
	v_cvt_pk_bf16_f32 v19, v22, v23
	v_cvt_pk_bf16_f32 v20, v26, v27
	v_cvt_pk_bf16_f32 v21, v24, v25
	s_waitcnt lgkmcnt(0)
	v_add_f32_e32 v16, v16, v17
	ds_bpermute_b32 v17, v194, v16
	global_store_dwordx4 v[42:43], v[18:21], off offset:64
	s_and_saveexec_b64 s[46:47], vcc
	s_cbranch_execz .LBB0_399
	v_lshlrev_b64 v[18:19], 6, v[32:33]
	v_lshl_add_u64 v[18:19], s[6:7], 0, v[18:19]
	v_lshl_add_u64 v[18:19], s[44:45], 2, v[18:19]
	s_lshl_b32 s20, s29, 2
	v_lshl_add_u64 v[18:19], v[18:19], 0, s[20:21]
	s_waitcnt lgkmcnt(0)
	v_add_f32_e32 v16, v16, v17
	global_store_dword v[18:19], v16, off
.LBB0_399:
	s_or_b64 exec, exec, s[46:47]
	v_add_u32_e32 v16, 0xb0, v142
	s_waitcnt lgkmcnt(0)
	v_ashrrev_i32_e32 v17, 31, v16
	v_lshlrev_b64 v[18:19], 10, v[16:17]
	v_lshl_add_u64 v[26:27], v[18:19], 0, v[140:141]
	v_lshl_add_u64 v[28:29], v[26:27], 2, s[12:13]
	v_lshl_add_u64 v[26:27], v[26:27], 1, s[16:17]
	v_mov_b64_e32 v[20:21], v[14:15]
	v_mov_b64_e32 v[24:25], v[10:11]
	v_mov_b64_e32 v[22:23], v[8:9]
	v_cvt_pk_bf16_f32 v8, v12, v13
	v_cvt_pk_bf16_f32 v9, v20, v21
	v_cvt_pk_bf16_f32 v10, v22, v23
	v_cvt_pk_bf16_f32 v11, v24, v25
	global_store_dwordx4 v[26:27], v[8:11], off
	s_nop 0
	v_mul_f32_e32 v19, v13, v13
	v_mul_f32_e32 v21, v21, v21
	v_mul_f32_e32 v23, v23, v23
	v_mul_f32_e32 v25, v25, v25
	v_fmac_f32_e32 v19, v12, v12
	v_fmac_f32_e32 v21, v20, v20
	v_fmac_f32_e32 v23, v22, v22
	v_fmac_f32_e32 v25, v24, v24
	v_add_f32_e32 v18, v19, v21
	v_add_f32_e32 v19, v23, v25
	v_add_f32_e32 v18, v18, v19
	v_mov_b64_e32 v[8:9], v[2:3]
	v_mov_b64_e32 v[10:11], v[0:1]
	v_mul_f32_e32 v0, v5, v5
	v_mul_f32_e32 v1, v7, v7
	v_mul_f32_e32 v2, v11, v11
	v_mul_f32_e32 v3, v9, v9
	v_fmac_f32_e32 v0, v4, v4
	v_fmac_f32_e32 v1, v6, v6
	v_fmac_f32_e32 v2, v10, v10
	v_fmac_f32_e32 v3, v8, v8
	v_add_f32_e32 v0, v0, v1
	v_add_f32_e32 v1, v2, v3
	v_add_f32_e32 v0, v0, v1
	v_add_f32_e32 v0, v18, v0
	ds_bpermute_b32 v1, v193, v0
	v_cvt_pk_bf16_f32 v2, v4, v5
	v_cvt_pk_bf16_f32 v3, v6, v7
	v_cvt_pk_bf16_f32 v4, v10, v11
	v_cvt_pk_bf16_f32 v5, v8, v9
	s_waitcnt lgkmcnt(0)
	v_add_f32_e32 v0, v0, v1
	ds_bpermute_b32 v1, v194, v0
	global_store_dwordx4 v[26:27], v[2:5], off offset:64
	s_and_saveexec_b64 s[46:47], vcc
	s_cbranch_execz .LBB0_401
	v_lshlrev_b64 v[2:3], 6, v[16:17]
	v_lshl_add_u64 v[2:3], s[6:7], 0, v[2:3]
	v_lshl_add_u64 v[2:3], s[44:45], 2, v[2:3]
	s_lshl_b32 s20, s29, 2
	v_lshl_add_u64 v[2:3], v[2:3], 0, s[20:21]
	s_waitcnt lgkmcnt(0)
	v_add_f32_e32 v0, v0, v1
	global_store_dword v[2:3], v0, off
